# S5 output stage stagger: waves 4-7 delayed by s_sleep 12
# speedup vs baseline: 1.0015x; 1.0015x over previous
; #define LAS __attribute__((address_space(3)))
; #define S5_LAUNDER() int tid_ = tid0, lane_ = lane0; asm volatile("" : "+v"(tid_), "+v"(lane_)); const int tid = tid_, lane = lane_, fr = lane & 15, fq = lane >> 4; (void)tid; (void)fr; (void)fq
; __device__ __forceinline__ void s5_prompt_item_mfma(LAS unsigned char* lds, int tid0, int lane0, int wave, int n, int g, const bf16* USg, const bf16* FTg, const bf16* WTg, const bf16* GTg, ...
;     ...
;     S5_LAUNDER();
; #pragma unroll
;     for (int it = 0; it < 4; ++it) { const int q = tid + 512 * it; *(LAS v4u*)(lds + R2_OFF + q * 16) = ftq[it]; }
;     const f32x4 dk = *(const f32x4*)(dsk + 4 * fq);
;     __syncthreads();
;     bf16x8 hbv[4][4];
; #pragma unroll
;     for (int kk = 0; kk < 4; ++kk)
; #pragma unroll
;         for (int cb = 0; cb < 4; ++cb) hbv[kk][cb] = *(const LAS bf16x8*)(lds + HP_OFF + (16 * cb + fr) * 272 + 64 * kk + 16 * fq);
.LBB0_852:
	s_or_b64 exec, exec, s[54:55]
	v_mov_b32_e32 v201, v196
	v_mov_b32_e32 v2, v192
	s_lshl_b32 s10, s65, 6
	s_barrier
	s_add_u32 s10, s52, s10
	v_ashrrev_i32_e32 v202, 4, v201
	v_lshlrev_b32_e32 v194, 2, v202
	s_addc_u32 s11, s53, 0
	v_ashrrev_i32_e32 v195, 31, v194
	v_lshl_add_u64 v[20:21], v[194:195], 2, s[10:11]
	global_load_dwordx4 v[20:23], v[20:21], off
	s_add_i32 s10, 0, 0x10800
	v_and_b32_e32 v203, 15, v201
	v_lshl_add_u32 v2, v2, 4, s10
	s_waitcnt vmcnt(20)
	ds_write_b128 v2, v[24:27]
	s_waitcnt vmcnt(19)
	ds_write_b128 v2, v[28:31] offset:8192
	s_waitcnt vmcnt(18)
	ds_write_b128 v2, v[32:35] offset:16384
	s_waitcnt vmcnt(17)
	ds_write_b128 v2, v[36:39] offset:24576
	v_and_b32_e32 v2, -16, v201
	s_add_i32 s11, 0, 0x18c00
	v_mul_u32_u24_e32 v24, 0x110, v203
	v_add3_u32 v2, s11, v2, v24
	s_waitcnt lgkmcnt(0)
	s_barrier
	v_readfirstlane_b32 s99, v192
	s_nop 3
	s_lshr_b32 s99, s99, 6
	s_cmp_lt_u32 s99, 4
	s_cbranch_scc1 .Ls5_stag
	s_sleep 12
